# in-projection epilogue: waves whose two 128-column halves carry no 64-wide q/k head skip the sum-of-squares stage (barrier kept)
# speedup vs baseline: 1.0066x; 1.0042x over previous
; #define LAS __attribute__((address_space(3)))
;     __device__ __forceinline__ void operator()(const f32x4 (&acc)[2][2][4][2], const Unit& u, int wr, int wc, int fr, int fq) const {
;     ...
; #pragma unroll
;         for (int ai = 0; ai < 2; ++ai)
; #pragma unroll
;             for (int m = 0; m < 4; ++m)
; #pragma unroll
;                 for (int bj = 0; bj < 2; ++bj) {
;                     const f32x4 v0 = acc[ai][bj][m][0], v1 = acc[ai][bj][m][1];
;                     float t = v0[0] * v0[0] + v0[1] * v0[1] + v0[2] * v0[2] + v0[3] * v0[3] + v1[0] * v1[0] + v1[1] * v1[1] + v1[2] * v1[2] + v1[3] * v1[3];
;                     t += __shfl_xor(t, 16); t += __shfl_xor(t, 32);
;                     if (fq == 0) *(LAS float*)(Pb + pown + ((ai * 4 + m) * 2 + bj) * 64) = t;
;                 }
;         asm volatile("s_waitcnt lgkmcnt(0)" ::: "memory"); __builtin_amdgcn_s_barrier(); asm volatile("" ::: "memory");
.LBB0_853:
	s_or_b64 vcc, s[58:59], s[54:55]
	s_cmp_eq_u64 vcc, 0
	s_cbranch_scc1 .Lmy_norm_skip
	v_mul_f32_e32 v145, v127, v127
	v_fmac_f32_e32 v145, v126, v126
	v_fmac_f32_e32 v145, v128, v128
	v_fmac_f32_e32 v145, v129, v129
	v_fmac_f32_e32 v145, v122, v122
	v_cmp_lt_i32_e32 vcc, v204, v199
	v_fmac_f32_e32 v145, v123, v123
	v_fmac_f32_e32 v145, v124, v124
	v_cndmask_b32_e32 v0, v197, v204, vcc
	v_lshlrev_b32_e32 v0, 2, v0
	v_fmac_f32_e32 v145, v125, v125
	v_mov_b32_e32 v146, v145
	s_nop 1
	v_permlane16_swap_b32_e32 v145, v146
	v_add_f32_e32 v145, v145, v146
	v_cmp_lt_i32_e32 vcc, v205, v199
	v_mov_b32_e32 v160, v155
	v_mov_b32_e32 v159, v156
	v_cndmask_b32_e32 v144, v197, v205, vcc
	v_lshlrev_b32_e32 v144, 2, v144
	v_mov_b32_e32 v146, v145
	s_nop 1
	v_permlane32_swap_b32_e32 v145, v146
	s_and_saveexec_b64 s[40:41], s[36:37]
	s_cbranch_execz .LBB0_855
	v_add_f32_e32 v145, v145, v146
	v_add_u32_e32 v146, 0, v160
	v_add_u32_e32 v146, 0x21900, v146
	ds_write_b32 v146, v145

;     __device__ __forceinline__ void operator()(const f32x4 (&acc)[2][2][4][2], const Unit& u, int wr, int wc, int fr, int fq) const {
;     ...
;         asm volatile("s_waitcnt lgkmcnt(0)" ::: "memory"); __builtin_amdgcn_s_barrier(); asm volatile("" ::: "memory");
; #pragma unroll
;         for (int bj = 0; bj < 2; ++bj) {
;             f32x4 g0 = (f32x4){1.f, 1.f, 1.f, 1.f}, g1 = g0;
;             if (gp[bj]) { const float* g = gp[bj] + (wc & 1) * 32 + fq * 8; g0 = *(const f32x4*)g * sc[bj]; g1 = *(const f32x4*)(g + 4) * sc[bj]; }
.Lmy_norm_skip:
	s_waitcnt lgkmcnt(0)
	s_barrier
	s_cmp_lg_u64 s[58:59], 0
	s_cselect_b64 s[60:61], -1, 0
	s_cmp_eq_u64 s[58:59], 0
	v_lshlrev_b32_e32 v0, 2, v138
	s_cbranch_scc1 .LBB0_922
	s_lshl_b32 s21, s63, 2
	s_add_u32 s22, s58, s21
	s_addc_u32 s23, s59, 0
	s_waitcnt lgkmcnt(0)
	v_lshl_add_u64 v[144:145], s[22:23], 0, v[0:1]
	flat_load_dwordx4 v[146:149], v[144:145]
	flat_load_dwordx4 v[150:153], v[144:145] offset:16
	s_waitcnt vmcnt(0) lgkmcnt(0)
	v_pk_mul_f32 v[144:145], s[56:57], v[148:149] op_sel_hi:[0,1]
	v_pk_mul_f32 v[148:149], s[56:57], v[146:147] op_sel_hi:[0,1]
	v_pk_mul_f32 v[146:147], s[56:57], v[152:153] op_sel_hi:[0,1]
	v_pk_mul_f32 v[150:151], s[56:57], v[150:151] op_sel_hi:[0,1]
	v_cndmask_b32_e64 v152, 0, 1, s[60:61]
	v_cmp_ne_u32_e64 s[40:41], 1, v152
	s_andn2_b64 vcc, exec, s[60:61]
	s_cbranch_vccnz .LBB0_888
